# P4 fused epilogue: final_w vectors loaded once instead of 32 reloads, the vmcnt(0) drains that serialised the output stores removed (on top of pipelined attention v13)
# speedup vs baseline: 1.0241x; 1.0016x over previous
;     DI void fused(pg8::f32x4 (&acc)[2][2][4][2], const pg8::Unit& u, int wr, int wc, int fr, int fq, PG8_LAS unsigned char* lds, int wid, int lane) const {
;     ...
; #pragma unroll
;         for (int ai = 0; ai < 2; ++ai)
; #pragma unroll
;             for (int m = 0; m < 4; ++m) {
;                 const size_t tok = (size_t)u.pm * 256 + ai * 128 + wr * 64 + m * 16 + fr;
;                 const f32x4* sp = (const f32x4*)(ssqh + tok * 16);
;                 const f32x4 a = sp[0], b2 = sp[1], c = sp[2], d = sp[3];
;                 const float s = ((a.x + a.y) + (a.z + a.w)) + ((b2.x + b2.y) + (b2.z + b2.w)) + ((c.x + c.y) + (c.z + c.w)) + ((d.x + d.y) + (d.z + d.w));
;                 const float rstd = 1.0f / sqrtf(s * (1.0f / 1024.0f) + EPS);
; #pragma unroll
;                 for (int bj = 0; bj < 2; ++bj)
; #pragma unroll
;                     for (int n = 0; n < 2; ++n) {
;                         const int col = u.pn * 256 + bj * 128 + wc * 32 + n * 16 + 4 * fq;
;                         const f32x4 w = *(const f32x4*)(fw + col);
;                         f32x4 o = acc[ai][bj][m][n];
;                         o.x = o.x * rstd * w.x; o.y = o.y * rstd * w.y; o.z = o.z * rstd * w.z; o.w = o.w * rstd * w.w;
;                         __builtin_nontemporal_store(o, (f32x4*)(out + tok * 1024 + col));
;                     }
;             }
.LBB0_2033:
	s_or_b64 exec, exec, s[6:7]
	v_lshl_add_u64 v[128:129], s[2:3], 0, v[156:157]
	s_barrier
	global_load_dwordx4 v[166:169], v[128:129], off
	global_load_dwordx4 v[170:173], v[128:129], off offset:16
	global_load_dwordx4 v[174:177], v[128:129], off offset:32
	global_load_dwordx4 v[178:181], v[128:129], off offset:48
	v_or_b32_e32 v128, s14, v164
	v_or_b32_e32 v128, s4, v128
	v_ashrrev_i32_e32 v129, 31, v128
	v_readlane_b32 s4, v236, 17
	v_lshlrev_b64 v[156:157], 2, v[128:129]
	v_readlane_b32 s18, v236, 31
	v_readlane_b32 s19, v236, 32
	v_mov_b32_e32 v162, 0x3727c5ac
	s_mov_b32 s4, 0xf800000
	v_lshl_add_u64 v[128:129], s[18:19], 0, v[156:157]
	global_load_dwordx4 v[186:189], v[128:129], off
	global_load_dwordx4 v[190:193], v[128:129], off offset:64
	global_load_dwordx4 v[194:197], v[128:129], off offset:512
	global_load_dwordx4 v[198:201], v[128:129], off offset:576
	v_lshl_add_u64 v[130:131], s[68:69], 0, v[130:131]
	v_lshl_add_u64 v[130:131], v[130:131], 0, v[156:157]
	v_lshl_add_u64 v[112:113], s[68:69], 0, v[112:113]
	v_lshl_add_u64 v[96:97], s[68:69], 0, v[96:97]
	v_lshl_add_u64 v[96:97], v[96:97], 0, v[156:157]
	v_lshl_add_u64 v[80:81], s[68:69], 0, v[80:81]
	v_lshl_add_u64 v[64:65], s[68:69], 0, v[64:65]
	v_lshl_add_u64 v[48:49], s[68:69], 0, v[48:49]
	v_lshl_add_u64 v[32:33], s[68:69], 0, v[32:33]
	v_lshl_add_u64 v[16:17], s[68:69], 0, v[16:17]
	v_lshl_add_u64 v[16:17], v[16:17], 0, v[156:157]
	v_readlane_b32 s5, v236, 18
	v_readlane_b32 s6, v236, 19
	v_readlane_b32 s7, v236, 20
	v_readlane_b32 s8, v236, 21
	v_readlane_b32 s9, v236, 22
	v_readlane_b32 s10, v236, 23
	v_readlane_b32 s11, v236, 24
	v_readlane_b32 s12, v236, 25
	v_readlane_b32 s13, v236, 26
	v_readlane_b32 s14, v236, 27
	v_readlane_b32 s15, v236, 28
	v_readlane_b32 s16, v236, 29
	v_readlane_b32 s17, v236, 30
	s_waitcnt vmcnt(7)
	v_mov_b32_e32 v164, v167
	v_mov_b32_e32 v165, v168
	v_mov_b32_e32 v167, v169
	s_waitcnt vmcnt(6)
	v_mov_b32_e32 v168, v171
	v_mov_b32_e32 v169, v172
	v_mov_b32_e32 v171, v173
	v_pk_add_f32 v[164:165], v[164:165], v[166:167]
	v_pk_add_f32 v[166:167], v[168:169], v[170:171]
	v_pk_add_f32 v[164:165], v[164:165], v[164:165] op_sel:[0,1] op_sel_hi:[1,0]
	v_pk_add_f32 v[166:167], v[166:167], v[166:167] op_sel:[0,1] op_sel_hi:[1,0]
	s_waitcnt vmcnt(5)
	v_add_f32_e32 v172, v174, v175
	v_add_f32_e32 v174, v176, v177
	s_waitcnt vmcnt(4)
	v_mov_b32_e32 v173, v180
	v_mov_b32_e32 v175, v181
	v_mov_b32_e32 v165, v178
	v_mov_b32_e32 v167, v179
	v_pk_add_f32 v[168:169], v[172:173], v[174:175]
	v_pk_add_f32 v[164:165], v[164:165], v[166:167]
	s_nop 0
	v_pk_add_f32 v[164:165], v[164:165], v[168:169]
	s_nop 0
	v_add_f32_e32 v163, v164, v165
	v_fmamk_f32 v163, v163, 0x3a800000, v162
	v_mul_f32_e32 v164, 0x4f800000, v163
	v_cmp_gt_f32_e32 vcc, s4, v163
	s_nop 1
	v_cndmask_b32_e32 v164, v163, v164, vcc
	v_sqrt_f32_e32 v165, v164
	v_mov_b32_e32 v163, 0x260
	v_add_u32_e32 v166, -1, v165
	v_add_u32_e32 v167, 1, v165
	v_fma_f32 v168, -v166, v165, v164
	v_fma_f32 v169, -v167, v165, v164
	v_cmp_ge_f32_e64 s[0:1], 0, v168
	s_nop 1
	v_cndmask_b32_e64 v165, v165, v166, s[0:1]
	v_cmp_lt_f32_e64 s[0:1], 0, v169
	s_nop 1
	v_cndmask_b32_e64 v165, v165, v167, s[0:1]
	v_mul_f32_e32 v166, 0x37800000, v165
	v_cndmask_b32_e32 v165, v165, v166, vcc
	v_cmp_class_f32_e32 vcc, v164, v163
	s_nop 1
	v_cndmask_b32_e32 v164, v165, v164, vcc
	v_div_scale_f32 v165, s[0:1], v164, v164, 1.0
	v_rcp_f32_e32 v166, v165
	v_div_scale_f32 v167, vcc, 1.0, v164, 1.0
	v_fma_f32 v168, -v165, v166, 1.0
	v_fmac_f32_e32 v166, v168, v166
	v_mul_f32_e32 v168, v167, v166
	v_fma_f32 v169, -v165, v168, v167
	v_fmac_f32_e32 v168, v169, v166
	v_fma_f32 v165, -v165, v168, v167
	v_div_fmas_f32 v165, v165, v166, v168
	v_div_fixup_f32 v164, v165, v164, 1.0
	v_pk_mul_f32 v[166:167], v[152:153], v[164:165] op_sel_hi:[1,0]
	v_pk_mul_f32 v[150:151], v[150:151], v[164:165] op_sel_hi:[1,0]
	s_waitcnt vmcnt(3)
	v_pk_mul_f32 v[152:153], v[188:189], v[150:151]
	v_pk_mul_f32 v[150:151], v[186:187], v[166:167]
	global_store_dwordx4 v[130:131], v[150:153], off nt
	v_pk_mul_f32 v[166:167], v[146:147], v[164:165] op_sel_hi:[1,0]
	v_pk_mul_f32 v[146:147], v[148:149], v[164:165] op_sel_hi:[1,0]
	s_waitcnt vmcnt(3)
	v_pk_mul_f32 v[148:149], v[192:193], v[166:167]
	v_pk_mul_f32 v[146:147], v[190:191], v[146:147]
	global_store_dwordx4 v[130:131], v[146:149], off offset:64 nt
	v_pk_mul_f32 v[150:151], v[140:141], v[164:165] op_sel_hi:[1,0]
	v_pk_mul_f32 v[140:141], v[142:143], v[164:165] op_sel_hi:[1,0]
	s_waitcnt vmcnt(3)
	v_pk_mul_f32 v[142:143], v[196:197], v[150:151]
	v_pk_mul_f32 v[140:141], v[194:195], v[140:141]
	global_store_dwordx4 v[130:131], v[140:143], off offset:512 nt
	v_pk_mul_f32 v[146:147], v[136:137], v[164:165] op_sel_hi:[1,0]
	v_pk_mul_f32 v[136:137], v[138:139], v[164:165] op_sel_hi:[1,0]
	v_lshl_add_u64 v[150:151], s[2:3], 0, v[160:161]
	s_waitcnt vmcnt(3)
	v_pk_mul_f32 v[136:137], v[198:199], v[136:137]
	v_pk_mul_f32 v[138:139], v[200:201], v[146:147]
	global_store_dwordx4 v[130:131], v[136:139], off offset:576 nt
	s_nop 1
	global_load_dwordx4 v[136:139], v[150:151], off
	s_nop 0
	global_load_dwordx4 v[140:143], v[150:151], off offset:16
	global_load_dwordx4 v[146:149], v[150:151], off offset:32
	s_nop 0
	global_load_dwordx4 v[150:153], v[150:151], off offset:48
	s_nop 0
	s_waitcnt vmcnt(3)
	v_mov_b32_e32 v130, v137
	v_mov_b32_e32 v131, v138
	v_mov_b32_e32 v137, v139
	s_waitcnt vmcnt(2)
	v_mov_b32_e32 v138, v141
	v_mov_b32_e32 v139, v142
	v_mov_b32_e32 v141, v143
	v_pk_add_f32 v[130:131], v[130:131], v[136:137]
	v_pk_add_f32 v[136:137], v[138:139], v[140:141]
	v_pk_add_f32 v[130:131], v[130:131], v[130:131] op_sel:[0,1] op_sel_hi:[1,0]
	v_pk_add_f32 v[136:137], v[136:137], v[136:137] op_sel:[0,1] op_sel_hi:[1,0]
	s_waitcnt vmcnt(1)
;     DI void fused(pg8::f32x4 (&acc)[2][2][4][2], const pg8::Unit& u, int wr, int wc, int fr, int fq, PG8_LAS unsigned char* lds, int wid, int lane) const {
;     ...
; #pragma unroll
;         for (int ai = 0; ai < 2; ++ai)
; #pragma unroll
;             for (int m = 0; m < 4; ++m) {
;                 const size_t tok = (size_t)u.pm * 256 + ai * 128 + wr * 64 + m * 16 + fr;
;                 const f32x4* sp = (const f32x4*)(ssqh + tok * 16);
;                 const f32x4 a = sp[0], b2 = sp[1], c = sp[2], d = sp[3];
;                 const float s = ((a.x + a.y) + (a.z + a.w)) + ((b2.x + b2.y) + (b2.z + b2.w)) + ((c.x + c.y) + (c.z + c.w)) + ((d.x + d.y) + (d.z + d.w));
;                 const float rstd = 1.0f / sqrtf(s * (1.0f / 1024.0f) + EPS);
; #pragma unroll
;                 for (int bj = 0; bj < 2; ++bj)
; #pragma unroll
;                     for (int n = 0; n < 2; ++n) {
;                         const int col = u.pn * 256 + bj * 128 + wc * 32 + n * 16 + 4 * fq;
;                         const f32x4 w = *(const f32x4*)(fw + col);
;                         f32x4 o = acc[ai][bj][m][n];
;                         o.x = o.x * rstd * w.x; o.y = o.y * rstd * w.y; o.z = o.z * rstd * w.z; o.w = o.w * rstd * w.w;
;                         __builtin_nontemporal_store(o, (f32x4*)(out + tok * 1024 + col));
;                     }
;             }
	v_add_f32_e32 v142, v146, v147
	v_add_f32_e32 v146, v148, v149
	s_waitcnt vmcnt(0)
	v_mov_b32_e32 v143, v152
	v_mov_b32_e32 v147, v153
	v_mov_b32_e32 v131, v150
	v_mov_b32_e32 v137, v151
	v_pk_add_f32 v[138:139], v[142:143], v[146:147]
	v_pk_add_f32 v[130:131], v[130:131], v[136:137]
	s_nop 0
	v_pk_add_f32 v[130:131], v[130:131], v[138:139]
	s_nop 0
	v_add_f32_e32 v130, v130, v131
	v_fmamk_f32 v130, v130, 0x3a800000, v162
	v_mul_f32_e32 v131, 0x4f800000, v130
	v_cmp_gt_f32_e32 vcc, s4, v130
	s_nop 1
	v_cndmask_b32_e32 v130, v130, v131, vcc
	v_sqrt_f32_e32 v131, v130
	s_nop 0
	v_add_u32_e32 v136, -1, v131
	v_add_u32_e32 v137, 1, v131
	v_fma_f32 v138, -v136, v131, v130
	v_fma_f32 v139, -v137, v131, v130
	v_cmp_ge_f32_e64 s[0:1], 0, v138
	s_nop 1
	v_cndmask_b32_e64 v131, v131, v136, s[0:1]
	v_cmp_lt_f32_e64 s[0:1], 0, v139
	s_nop 1
	v_cndmask_b32_e64 v131, v131, v137, s[0:1]
	v_mul_f32_e32 v136, 0x37800000, v131
	v_cndmask_b32_e32 v131, v131, v136, vcc
	v_cmp_class_f32_e32 vcc, v130, v163
	v_lshl_add_u64 v[136:137], v[112:113], 0, v[156:157]
	s_nop 0
	v_cndmask_b32_e32 v130, v131, v130, vcc
	v_div_scale_f32 v131, s[0:1], v130, v130, 1.0
	v_rcp_f32_e32 v138, v131
	v_div_scale_f32 v112, vcc, 1.0, v130, 1.0
	v_fma_f32 v113, -v131, v138, 1.0
	v_fmac_f32_e32 v138, v113, v138
	v_mul_f32_e32 v113, v112, v138
	v_fma_f32 v139, -v131, v113, v112
	v_fmac_f32_e32 v113, v139, v138
	v_fma_f32 v112, -v131, v113, v112
	v_div_fmas_f32 v112, v112, v138, v113
	v_div_fixup_f32 v112, v112, v130, 1.0
	v_pk_mul_f32 v[130:131], v[134:135], v[112:113] op_sel_hi:[1,0]
	v_pk_mul_f32 v[132:133], v[132:133], v[112:113] op_sel_hi:[1,0]
	v_pk_mul_f32 v[130:131], v[186:187], v[130:131]
	v_pk_mul_f32 v[132:133], v[188:189], v[132:133]
	global_store_dwordx4 v[136:137], v[130:133], off nt
	v_pk_mul_f32 v[134:135], v[124:125], v[112:113] op_sel_hi:[1,0]
	v_pk_mul_f32 v[124:125], v[126:127], v[112:113] op_sel_hi:[1,0]
	v_pk_mul_f32 v[114:115], v[114:115], v[112:113] op_sel_hi:[1,0]
	v_pk_mul_f32 v[124:125], v[190:191], v[124:125]
	v_pk_mul_f32 v[126:127], v[192:193], v[134:135]
	global_store_dwordx4 v[136:137], v[124:127], off offset:64 nt
	v_pk_mul_f32 v[130:131], v[120:121], v[112:113] op_sel_hi:[1,0]
	v_pk_mul_f32 v[120:121], v[122:123], v[112:113] op_sel_hi:[1,0]
	v_pk_mul_f32 v[112:113], v[116:117], v[112:113] op_sel_hi:[1,0]
	v_pk_mul_f32 v[120:121], v[194:195], v[120:121]
	v_pk_mul_f32 v[122:123], v[196:197], v[130:131]
	global_store_dwordx4 v[136:137], v[120:123], off offset:512 nt
	v_lshl_add_u64 v[130:131], s[2:3], 0, v[158:159]
	v_pk_mul_f32 v[112:113], v[198:199], v[112:113]
	v_pk_mul_f32 v[114:115], v[200:201], v[114:115]
	global_store_dwordx4 v[136:137], v[112:115], off offset:576 nt
	s_nop 1
	global_load_dwordx4 v[112:115], v[130:131], off
	s_nop 0
	global_load_dwordx4 v[120:123], v[130:131], off offset:16
	global_load_dwordx4 v[124:127], v[130:131], off offset:32
	s_nop 0
	global_load_dwordx4 v[130:133], v[130:131], off offset:48
	s_nop 0
	s_waitcnt vmcnt(3)
	v_mov_b32_e32 v116, v113
	v_mov_b32_e32 v117, v114
	v_mov_b32_e32 v113, v115
	s_waitcnt vmcnt(2)
	v_mov_b32_e32 v114, v121
	v_mov_b32_e32 v115, v122
	v_mov_b32_e32 v121, v123
	v_pk_add_f32 v[112:113], v[116:117], v[112:113]
	v_pk_add_f32 v[114:115], v[114:115], v[120:121]
	v_pk_add_f32 v[112:113], v[112:113], v[112:113] op_sel:[0,1] op_sel_hi:[1,0]
	v_pk_add_f32 v[114:115], v[114:115], v[114:115] op_sel:[0,1] op_sel_hi:[1,0]
	s_waitcnt vmcnt(1)
	v_add_f32_e32 v122, v124, v125
	v_add_f32_e32 v124, v126, v127
	s_waitcnt vmcnt(0)
	v_mov_b32_e32 v123, v132
	v_mov_b32_e32 v125, v133
	v_mov_b32_e32 v113, v130
	v_mov_b32_e32 v115, v131
	v_pk_add_f32 v[116:117], v[122:123], v[124:125]
	v_pk_add_f32 v[112:113], v[112:113], v[114:115]
	s_nop 0
	v_pk_add_f32 v[112:113], v[112:113], v[116:117]
	s_nop 0
	v_add_f32_e32 v112, v112, v113
	v_fmamk_f32 v112, v112, 0x3a800000, v162
	v_mul_f32_e32 v113, 0x4f800000, v112
	v_cmp_gt_f32_e32 vcc, s4, v112
	s_nop 1
	v_cndmask_b32_e32 v112, v112, v113, vcc
	v_sqrt_f32_e32 v113, v112
	s_nop 0
	v_add_u32_e32 v114, -1, v113
	v_add_u32_e32 v115, 1, v113
	v_fma_f32 v116, -v114, v113, v112
	v_fma_f32 v117, -v115, v113, v112
	v_cmp_ge_f32_e64 s[0:1], 0, v116
	s_nop 1
	v_cndmask_b32_e64 v113, v113, v114, s[0:1]
	v_cmp_lt_f32_e64 s[0:1], 0, v117
	s_nop 1
	v_cndmask_b32_e64 v113, v113, v115, s[0:1]
	v_mul_f32_e32 v114, 0x37800000, v113
	v_cndmask_b32_e32 v113, v113, v114, vcc
	v_cmp_class_f32_e32 vcc, v112, v163
	s_nop 1
	v_cndmask_b32_e32 v112, v113, v112, vcc
	v_div_scale_f32 v113, s[0:1], v112, v112, 1.0
	v_rcp_f32_e32 v114, v113
	v_div_scale_f32 v115, vcc, 1.0, v112, 1.0
	v_fma_f32 v116, -v113, v114, 1.0
	v_fmac_f32_e32 v114, v116, v114
	v_mul_f32_e32 v116, v115, v114
	v_fma_f32 v117, -v113, v116, v115
	v_fmac_f32_e32 v116, v117, v114
	v_fma_f32 v113, -v113, v116, v115
	v_div_fmas_f32 v113, v113, v114, v116
	v_div_fixup_f32 v112, v113, v112, 1.0
	v_pk_mul_f32 v[114:115], v[110:111], v[112:113] op_sel_hi:[1,0]
	v_pk_mul_f32 v[108:109], v[108:109], v[112:113] op_sel_hi:[1,0]
	v_lshl_add_u64 v[116:117], s[2:3], 0, v[154:155]
	v_pk_mul_f32 v[110:111], v[188:189], v[108:109]
	v_pk_mul_f32 v[108:109], v[186:187], v[114:115]
	global_store_dwordx4 v[96:97], v[108:111], off nt
	v_pk_mul_f32 v[114:115], v[104:105], v[112:113] op_sel_hi:[1,0]
	v_pk_mul_f32 v[104:105], v[106:107], v[112:113] op_sel_hi:[1,0]
	v_pk_mul_f32 v[106:107], v[192:193], v[114:115]
	v_pk_mul_f32 v[104:105], v[190:191], v[104:105]
	global_store_dwordx4 v[96:97], v[104:107], off offset:64 nt
	v_pk_mul_f32 v[108:109], v[100:101], v[112:113] op_sel_hi:[1,0]
	v_pk_mul_f32 v[100:101], v[102:103], v[112:113] op_sel_hi:[1,0]
	v_pk_mul_f32 v[102:103], v[196:197], v[108:109]
	v_pk_mul_f32 v[100:101], v[194:195], v[100:101]
	global_store_dwordx4 v[96:97], v[100:103], off offset:512 nt
	v_pk_mul_f32 v[104:105], v[92:93], v[112:113] op_sel_hi:[1,0]
	v_pk_mul_f32 v[92:93], v[94:95], v[112:113] op_sel_hi:[1,0]
	v_pk_mul_f32 v[94:95], v[200:201], v[104:105]
	v_pk_mul_f32 v[92:93], v[198:199], v[92:93]
	global_store_dwordx4 v[96:97], v[92:95], off offset:576 nt
	s_nop 1
	global_load_dwordx4 v[92:95], v[116:117], off
	s_nop 0
	global_load_dwordx4 v[100:103], v[116:117], off offset:16
	global_load_dwordx4 v[104:107], v[116:117], off offset:32
	global_load_dwordx4 v[108:111], v[116:117], off offset:48
	s_waitcnt vmcnt(3)
;     DI void fused(pg8::f32x4 (&acc)[2][2][4][2], const pg8::Unit& u, int wr, int wc, int fr, int fq, PG8_LAS unsigned char* lds, int wid, int lane) const {
;     ...
; #pragma unroll
;         for (int ai = 0; ai < 2; ++ai)
; #pragma unroll
;             for (int m = 0; m < 4; ++m) {
;                 const size_t tok = (size_t)u.pm * 256 + ai * 128 + wr * 64 + m * 16 + fr;
;                 const f32x4* sp = (const f32x4*)(ssqh + tok * 16);
;                 const f32x4 a = sp[0], b2 = sp[1], c = sp[2], d = sp[3];
;                 const float s = ((a.x + a.y) + (a.z + a.w)) + ((b2.x + b2.y) + (b2.z + b2.w)) + ((c.x + c.y) + (c.z + c.w)) + ((d.x + d.y) + (d.z + d.w));
;                 const float rstd = 1.0f / sqrtf(s * (1.0f / 1024.0f) + EPS);
; #pragma unroll
;                 for (int bj = 0; bj < 2; ++bj)
; #pragma unroll
;                     for (int n = 0; n < 2; ++n) {
;                         const int col = u.pn * 256 + bj * 128 + wc * 32 + n * 16 + 4 * fq;
;                         const f32x4 w = *(const f32x4*)(fw + col);
;                         f32x4 o = acc[ai][bj][m][n];
;                         o.x = o.x * rstd * w.x; o.y = o.y * rstd * w.y; o.z = o.z * rstd * w.z; o.w = o.w * rstd * w.w;
;                         __builtin_nontemporal_store(o, (f32x4*)(out + tok * 1024 + col));
;                     }
;             }
	v_mov_b32_e32 v96, v93
	v_mov_b32_e32 v97, v94
	v_mov_b32_e32 v93, v95
	s_waitcnt vmcnt(2)
	v_mov_b32_e32 v94, v101
	v_mov_b32_e32 v95, v102
	v_mov_b32_e32 v101, v103
	v_pk_add_f32 v[92:93], v[96:97], v[92:93]
	v_pk_add_f32 v[94:95], v[94:95], v[100:101]
	v_pk_add_f32 v[92:93], v[92:93], v[92:93] op_sel:[0,1] op_sel_hi:[1,0]
	v_pk_add_f32 v[94:95], v[94:95], v[94:95] op_sel:[0,1] op_sel_hi:[1,0]
	s_waitcnt vmcnt(1)
	v_add_f32_e32 v102, v104, v105
	v_add_f32_e32 v104, v106, v107
	s_waitcnt vmcnt(0)
	v_mov_b32_e32 v103, v110
	v_mov_b32_e32 v105, v111
	v_mov_b32_e32 v93, v108
	v_mov_b32_e32 v95, v109
	v_pk_add_f32 v[96:97], v[102:103], v[104:105]
	v_pk_add_f32 v[92:93], v[92:93], v[94:95]
	s_nop 0
	v_pk_add_f32 v[92:93], v[92:93], v[96:97]
	s_nop 0
	v_add_f32_e32 v92, v92, v93
	v_fmamk_f32 v92, v92, 0x3a800000, v162
	v_mul_f32_e32 v93, 0x4f800000, v92
	v_cmp_gt_f32_e32 vcc, s4, v92
	s_nop 1
	v_cndmask_b32_e32 v92, v92, v93, vcc
	v_sqrt_f32_e32 v93, v92
	s_nop 0
	v_add_u32_e32 v94, -1, v93
	v_add_u32_e32 v95, 1, v93
	v_fma_f32 v96, -v94, v93, v92
	v_fma_f32 v97, -v95, v93, v92
	v_cmp_ge_f32_e64 s[0:1], 0, v96
	s_nop 1
	v_cndmask_b32_e64 v93, v93, v94, s[0:1]
	v_cmp_lt_f32_e64 s[0:1], 0, v97
	s_nop 1
	v_cndmask_b32_e64 v93, v93, v95, s[0:1]
	v_mul_f32_e32 v94, 0x37800000, v93
	v_cndmask_b32_e32 v93, v93, v94, vcc
	v_cmp_class_f32_e32 vcc, v92, v163
	s_nop 1
	v_cndmask_b32_e32 v94, v93, v92, vcc
	v_div_scale_f32 v95, s[0:1], v94, v94, 1.0
	v_rcp_f32_e32 v96, v95
	v_lshl_add_u64 v[92:93], v[80:81], 0, v[156:157]
	v_div_scale_f32 v80, vcc, 1.0, v94, 1.0
	v_fma_f32 v81, -v95, v96, 1.0
	v_fmac_f32_e32 v96, v81, v96
	v_mul_f32_e32 v81, v80, v96
	v_fma_f32 v97, -v95, v81, v80
	v_fmac_f32_e32 v81, v97, v96
	v_fma_f32 v80, -v95, v81, v80
	v_div_fmas_f32 v80, v80, v96, v81
	v_div_fixup_f32 v94, v80, v94, 1.0
	v_pk_mul_f32 v[80:81], v[90:91], v[94:95] op_sel_hi:[1,0]
	v_pk_mul_f32 v[88:89], v[88:89], v[94:95] op_sel_hi:[1,0]
	v_lshl_add_u64 v[96:97], s[2:3], 0, v[144:145]
	v_pk_mul_f32 v[90:91], v[188:189], v[88:89]
	v_pk_mul_f32 v[88:89], v[186:187], v[80:81]
	global_store_dwordx4 v[92:93], v[88:91], off nt
	v_pk_mul_f32 v[80:81], v[84:85], v[94:95] op_sel_hi:[1,0]
	v_pk_mul_f32 v[84:85], v[86:87], v[94:95] op_sel_hi:[1,0]
	v_pk_mul_f32 v[86:87], v[192:193], v[80:81]
	v_pk_mul_f32 v[84:85], v[190:191], v[84:85]
	global_store_dwordx4 v[92:93], v[84:87], off offset:64 nt
	v_pk_mul_f32 v[80:81], v[78:79], v[94:95] op_sel_hi:[1,0]
	v_pk_mul_f32 v[78:79], v[82:83], v[94:95] op_sel_hi:[1,0]
	v_pk_mul_f32 v[82:83], v[72:73], v[94:95] op_sel_hi:[1,0]
	v_pk_mul_f32 v[72:73], v[74:75], v[94:95] op_sel_hi:[1,0]
	v_pk_mul_f32 v[78:79], v[194:195], v[78:79]
	v_pk_mul_f32 v[80:81], v[196:197], v[80:81]
	global_store_dwordx4 v[92:93], v[78:81], off offset:512 nt
	v_pk_mul_f32 v[72:73], v[198:199], v[72:73]
	v_pk_mul_f32 v[74:75], v[200:201], v[82:83]
	global_store_dwordx4 v[92:93], v[72:75], off offset:576 nt
	s_nop 1
	global_load_dwordx4 v[72:75], v[96:97], off
	s_nop 0
	global_load_dwordx4 v[78:81], v[96:97], off offset:16
	global_load_dwordx4 v[82:85], v[96:97], off offset:32
	global_load_dwordx4 v[86:89], v[96:97], off offset:48
	s_waitcnt vmcnt(3)
	v_mov_b32_e32 v94, v73
	v_mov_b32_e32 v95, v74
	v_mov_b32_e32 v73, v75
	s_waitcnt vmcnt(2)
	v_mov_b32_e32 v74, v79
	v_mov_b32_e32 v75, v80
	v_mov_b32_e32 v79, v81
	v_pk_add_f32 v[72:73], v[94:95], v[72:73]
	v_pk_add_f32 v[74:75], v[74:75], v[78:79]
	v_pk_add_f32 v[72:73], v[72:73], v[72:73] op_sel:[0,1] op_sel_hi:[1,0]
	v_pk_add_f32 v[74:75], v[74:75], v[74:75] op_sel:[0,1] op_sel_hi:[1,0]
	s_waitcnt vmcnt(1)
	v_add_f32_e32 v80, v82, v83
	v_add_f32_e32 v82, v84, v85
	s_waitcnt vmcnt(0)
	v_mov_b32_e32 v81, v88
	v_mov_b32_e32 v83, v89
	v_mov_b32_e32 v73, v86
	v_mov_b32_e32 v75, v87
	v_pk_add_f32 v[78:79], v[80:81], v[82:83]
	v_pk_add_f32 v[72:73], v[72:73], v[74:75]
	s_nop 0
	v_pk_add_f32 v[72:73], v[72:73], v[78:79]
	s_nop 0
	v_add_f32_e32 v72, v72, v73
	v_fmamk_f32 v72, v72, 0x3a800000, v162
	v_mul_f32_e32 v73, 0x4f800000, v72
	v_cmp_gt_f32_e32 vcc, s4, v72
	s_nop 1
	v_cndmask_b32_e32 v72, v72, v73, vcc
	v_sqrt_f32_e32 v73, v72
	s_nop 0
	v_add_u32_e32 v74, -1, v73
	v_add_u32_e32 v75, 1, v73
	v_fma_f32 v78, -v74, v73, v72
	v_fma_f32 v79, -v75, v73, v72
	v_cmp_ge_f32_e64 s[0:1], 0, v78
	s_nop 1
	v_cndmask_b32_e64 v73, v73, v74, s[0:1]
	v_cmp_lt_f32_e64 s[0:1], 0, v79
	s_nop 1
	v_cndmask_b32_e64 v73, v73, v75, s[0:1]
	v_mul_f32_e32 v74, 0x37800000, v73
	v_cndmask_b32_e32 v73, v73, v74, vcc
	v_cmp_class_f32_e32 vcc, v72, v163
	s_nop 1
	v_cndmask_b32_e32 v74, v73, v72, vcc
	v_div_scale_f32 v75, s[0:1], v74, v74, 1.0
	v_rcp_f32_e32 v78, v75
	v_lshl_add_u64 v[72:73], v[64:65], 0, v[156:157]
	v_div_scale_f32 v64, vcc, 1.0, v74, 1.0
	v_fma_f32 v65, -v75, v78, 1.0
	v_fmac_f32_e32 v78, v65, v78
	v_mul_f32_e32 v65, v64, v78
	v_fma_f32 v79, -v75, v65, v64
	v_fmac_f32_e32 v65, v79, v78
	v_fma_f32 v64, -v75, v65, v64
	v_div_fmas_f32 v64, v64, v78, v65
	v_div_fixup_f32 v74, v64, v74, 1.0
	v_pk_mul_f32 v[64:65], v[70:71], v[74:75] op_sel_hi:[1,0]
	v_pk_mul_f32 v[68:69], v[68:69], v[74:75] op_sel_hi:[1,0]
	v_lshl_add_u64 v[78:79], s[2:3], 0, v[118:119]
	v_pk_mul_f32 v[70:71], v[188:189], v[68:69]
	v_pk_mul_f32 v[68:69], v[186:187], v[64:65]
	global_store_dwordx4 v[72:73], v[68:71], off nt
	v_pk_mul_f32 v[64:65], v[62:63], v[74:75] op_sel_hi:[1,0]
	v_pk_mul_f32 v[62:63], v[66:67], v[74:75] op_sel_hi:[1,0]
	v_pk_mul_f32 v[66:67], v[58:59], v[74:75] op_sel_hi:[1,0]
	v_pk_mul_f32 v[58:59], v[60:61], v[74:75] op_sel_hi:[1,0]
	v_pk_mul_f32 v[62:63], v[190:191], v[62:63]
	v_pk_mul_f32 v[64:65], v[192:193], v[64:65]
	global_store_dwordx4 v[72:73], v[62:65], off offset:64 nt
	v_pk_mul_f32 v[58:59], v[194:195], v[58:59]
	v_pk_mul_f32 v[60:61], v[196:197], v[66:67]
	global_store_dwordx4 v[72:73], v[58:61], off offset:512 nt
	v_pk_mul_f32 v[62:63], v[54:55], v[74:75] op_sel_hi:[1,0]
	v_pk_mul_f32 v[54:55], v[56:57], v[74:75] op_sel_hi:[1,0]
	v_pk_mul_f32 v[56:57], v[200:201], v[62:63]
	v_pk_mul_f32 v[54:55], v[198:199], v[54:55]
	global_store_dwordx4 v[72:73], v[54:57], off offset:576 nt
	s_nop 1
	global_load_dwordx4 v[54:57], v[78:79], off
	s_nop 0
	global_load_dwordx4 v[58:61], v[78:79], off offset:16
	global_load_dwordx4 v[62:65], v[78:79], off offset:32
	global_load_dwordx4 v[66:69], v[78:79], off offset:48
	s_waitcnt vmcnt(3)
;     DI void fused(pg8::f32x4 (&acc)[2][2][4][2], const pg8::Unit& u, int wr, int wc, int fr, int fq, PG8_LAS unsigned char* lds, int wid, int lane) const {
;     ...
; #pragma unroll
;         for (int ai = 0; ai < 2; ++ai)
; #pragma unroll
;             for (int m = 0; m < 4; ++m) {
;                 const size_t tok = (size_t)u.pm * 256 + ai * 128 + wr * 64 + m * 16 + fr;
;                 const f32x4* sp = (const f32x4*)(ssqh + tok * 16);
;                 const f32x4 a = sp[0], b2 = sp[1], c = sp[2], d = sp[3];
;                 const float s = ((a.x + a.y) + (a.z + a.w)) + ((b2.x + b2.y) + (b2.z + b2.w)) + ((c.x + c.y) + (c.z + c.w)) + ((d.x + d.y) + (d.z + d.w));
;                 const float rstd = 1.0f / sqrtf(s * (1.0f / 1024.0f) + EPS);
; #pragma unroll
;                 for (int bj = 0; bj < 2; ++bj)
; #pragma unroll
;                     for (int n = 0; n < 2; ++n) {
;                         const int col = u.pn * 256 + bj * 128 + wc * 32 + n * 16 + 4 * fq;
;                         const f32x4 w = *(const f32x4*)(fw + col);
;                         f32x4 o = acc[ai][bj][m][n];
;                         o.x = o.x * rstd * w.x; o.y = o.y * rstd * w.y; o.z = o.z * rstd * w.z; o.w = o.w * rstd * w.w;
;                         __builtin_nontemporal_store(o, (f32x4*)(out + tok * 1024 + col));
;                     }
;             }
	v_mov_b32_e32 v74, v55
	v_mov_b32_e32 v75, v56
	v_mov_b32_e32 v55, v57
	s_waitcnt vmcnt(2)
	v_mov_b32_e32 v56, v59
	v_mov_b32_e32 v57, v60
	v_mov_b32_e32 v59, v61
	v_pk_add_f32 v[54:55], v[74:75], v[54:55]
	v_pk_add_f32 v[56:57], v[56:57], v[58:59]
	v_pk_add_f32 v[54:55], v[54:55], v[54:55] op_sel:[0,1] op_sel_hi:[1,0]
	v_pk_add_f32 v[56:57], v[56:57], v[56:57] op_sel:[0,1] op_sel_hi:[1,0]
	s_waitcnt vmcnt(1)
	v_add_f32_e32 v60, v62, v63
	v_add_f32_e32 v62, v64, v65
	s_waitcnt vmcnt(0)
	v_mov_b32_e32 v61, v68
	v_mov_b32_e32 v63, v69
	v_mov_b32_e32 v55, v66
	v_mov_b32_e32 v57, v67
	v_pk_add_f32 v[58:59], v[60:61], v[62:63]
	v_pk_add_f32 v[54:55], v[54:55], v[56:57]
	s_nop 0
	v_pk_add_f32 v[54:55], v[54:55], v[58:59]
	s_nop 0
	v_add_f32_e32 v54, v54, v55
	v_fmamk_f32 v54, v54, 0x3a800000, v162
	v_mul_f32_e32 v55, 0x4f800000, v54
	v_cmp_gt_f32_e32 vcc, s4, v54
	s_nop 1
	v_cndmask_b32_e32 v54, v54, v55, vcc
	v_sqrt_f32_e32 v55, v54
	s_nop 0
	v_add_u32_e32 v56, -1, v55
	v_add_u32_e32 v57, 1, v55
	v_fma_f32 v58, -v56, v55, v54
	v_fma_f32 v59, -v57, v55, v54
	v_cmp_ge_f32_e64 s[0:1], 0, v58
	s_nop 1
	v_cndmask_b32_e64 v55, v55, v56, s[0:1]
	v_cmp_lt_f32_e64 s[0:1], 0, v59
	s_nop 1
	v_cndmask_b32_e64 v55, v55, v57, s[0:1]
	v_mul_f32_e32 v56, 0x37800000, v55
	v_cndmask_b32_e32 v55, v55, v56, vcc
	v_cmp_class_f32_e32 vcc, v54, v163
	s_nop 1
	v_cndmask_b32_e32 v56, v55, v54, vcc
	v_div_scale_f32 v57, s[0:1], v56, v56, 1.0
	v_rcp_f32_e32 v58, v57
	v_lshl_add_u64 v[54:55], v[48:49], 0, v[156:157]
	v_div_scale_f32 v48, vcc, 1.0, v56, 1.0
	v_fma_f32 v49, -v57, v58, 1.0
	v_fmac_f32_e32 v58, v49, v58
	v_mul_f32_e32 v49, v48, v58
	v_fma_f32 v59, -v57, v49, v48
	v_fmac_f32_e32 v49, v59, v58
	v_fma_f32 v48, -v57, v49, v48
	v_div_fmas_f32 v48, v48, v58, v49
	v_div_fixup_f32 v56, v48, v56, 1.0
	v_pk_mul_f32 v[48:49], v[52:53], v[56:57] op_sel_hi:[1,0]
	v_pk_mul_f32 v[50:51], v[50:51], v[56:57] op_sel_hi:[1,0]
	v_pk_mul_f32 v[48:49], v[186:187], v[48:49]
	v_pk_mul_f32 v[50:51], v[188:189], v[50:51]
	global_store_dwordx4 v[54:55], v[48:51], off nt
	v_pk_mul_f32 v[52:53], v[44:45], v[56:57] op_sel_hi:[1,0]
	v_pk_mul_f32 v[44:45], v[46:47], v[56:57] op_sel_hi:[1,0]
	v_lshl_add_u64 v[58:59], s[2:3], 0, v[98:99]
	v_pk_mul_f32 v[44:45], v[190:191], v[44:45]
	v_pk_mul_f32 v[46:47], v[192:193], v[52:53]
	global_store_dwordx4 v[54:55], v[44:47], off offset:64 nt
	v_pk_mul_f32 v[48:49], v[40:41], v[56:57] op_sel_hi:[1,0]
	v_pk_mul_f32 v[40:41], v[42:43], v[56:57] op_sel_hi:[1,0]
	v_pk_mul_f32 v[42:43], v[196:197], v[48:49]
	v_pk_mul_f32 v[40:41], v[194:195], v[40:41]
	global_store_dwordx4 v[54:55], v[40:43], off offset:512 nt
	v_pk_mul_f32 v[44:45], v[36:37], v[56:57] op_sel_hi:[1,0]
	v_pk_mul_f32 v[36:37], v[38:39], v[56:57] op_sel_hi:[1,0]
	v_pk_mul_f32 v[38:39], v[200:201], v[44:45]
	v_pk_mul_f32 v[36:37], v[198:199], v[36:37]
	global_store_dwordx4 v[54:55], v[36:39], off offset:576 nt
	s_nop 1
	global_load_dwordx4 v[36:39], v[58:59], off
	s_nop 0
	global_load_dwordx4 v[40:43], v[58:59], off offset:16
	global_load_dwordx4 v[44:47], v[58:59], off offset:32
	global_load_dwordx4 v[48:51], v[58:59], off offset:48
	s_waitcnt vmcnt(3)
	v_mov_b32_e32 v56, v37
	v_mov_b32_e32 v57, v38
	v_mov_b32_e32 v37, v39
	s_waitcnt vmcnt(2)
	v_mov_b32_e32 v38, v41
	v_mov_b32_e32 v39, v42
	v_mov_b32_e32 v41, v43
	v_pk_add_f32 v[36:37], v[56:57], v[36:37]
	v_pk_add_f32 v[38:39], v[38:39], v[40:41]
	v_pk_add_f32 v[36:37], v[36:37], v[36:37] op_sel:[0,1] op_sel_hi:[1,0]
	v_pk_add_f32 v[38:39], v[38:39], v[38:39] op_sel:[0,1] op_sel_hi:[1,0]
	s_waitcnt vmcnt(1)
	v_add_f32_e32 v42, v44, v45
	v_add_f32_e32 v44, v46, v47
	s_waitcnt vmcnt(0)
;     DI void fused(pg8::f32x4 (&acc)[2][2][4][2], const pg8::Unit& u, int wr, int wc, int fr, int fq, PG8_LAS unsigned char* lds, int wid, int lane) const {
;     ...
; #pragma unroll
;         for (int ai = 0; ai < 2; ++ai)
; #pragma unroll
;             for (int m = 0; m < 4; ++m) {
;                 const size_t tok = (size_t)u.pm * 256 + ai * 128 + wr * 64 + m * 16 + fr;
;                 const f32x4* sp = (const f32x4*)(ssqh + tok * 16);
;                 const f32x4 a = sp[0], b2 = sp[1], c = sp[2], d = sp[3];
;                 const float s = ((a.x + a.y) + (a.z + a.w)) + ((b2.x + b2.y) + (b2.z + b2.w)) + ((c.x + c.y) + (c.z + c.w)) + ((d.x + d.y) + (d.z + d.w));
;                 const float rstd = 1.0f / sqrtf(s * (1.0f / 1024.0f) + EPS);
; #pragma unroll
;                 for (int bj = 0; bj < 2; ++bj)
; #pragma unroll
;                     for (int n = 0; n < 2; ++n) {
;                         const int col = u.pn * 256 + bj * 128 + wc * 32 + n * 16 + 4 * fq;
;                         const f32x4 w = *(const f32x4*)(fw + col);
;                         f32x4 o = acc[ai][bj][m][n];
;                         o.x = o.x * rstd * w.x; o.y = o.y * rstd * w.y; o.z = o.z * rstd * w.z; o.w = o.w * rstd * w.w;
;                         __builtin_nontemporal_store(o, (f32x4*)(out + tok * 1024 + col));
;                     }
;             }
	v_mov_b32_e32 v43, v50
	v_mov_b32_e32 v45, v51
	v_mov_b32_e32 v37, v48
	v_mov_b32_e32 v39, v49
	v_pk_add_f32 v[40:41], v[42:43], v[44:45]
	v_pk_add_f32 v[36:37], v[36:37], v[38:39]
	s_nop 0
	v_pk_add_f32 v[36:37], v[36:37], v[40:41]
	s_nop 0
	v_add_f32_e32 v36, v36, v37
	v_fmamk_f32 v36, v36, 0x3a800000, v162
	v_mul_f32_e32 v37, 0x4f800000, v36
	v_cmp_gt_f32_e32 vcc, s4, v36
	s_nop 1
	v_cndmask_b32_e32 v36, v36, v37, vcc
	v_sqrt_f32_e32 v37, v36
	s_nop 0
	v_add_u32_e32 v38, -1, v37
	v_add_u32_e32 v39, 1, v37
	v_fma_f32 v40, -v38, v37, v36
	v_fma_f32 v41, -v39, v37, v36
	v_cmp_ge_f32_e64 s[0:1], 0, v40
	s_nop 1
	v_cndmask_b32_e64 v37, v37, v38, s[0:1]
	v_cmp_lt_f32_e64 s[0:1], 0, v41
	s_nop 1
	v_cndmask_b32_e64 v37, v37, v39, s[0:1]
	v_mul_f32_e32 v38, 0x37800000, v37
	v_cndmask_b32_e32 v37, v37, v38, vcc
	v_cmp_class_f32_e32 vcc, v36, v163
	s_nop 1
	v_cndmask_b32_e32 v38, v37, v36, vcc
	v_div_scale_f32 v39, s[0:1], v38, v38, 1.0
	v_rcp_f32_e32 v40, v39
	v_lshl_add_u64 v[36:37], v[32:33], 0, v[156:157]
	v_div_scale_f32 v32, vcc, 1.0, v38, 1.0
	v_fma_f32 v33, -v39, v40, 1.0
	v_fmac_f32_e32 v40, v33, v40
	v_mul_f32_e32 v33, v32, v40
	v_fma_f32 v41, -v39, v33, v32
	v_fmac_f32_e32 v33, v41, v40
	v_fma_f32 v32, -v39, v33, v32
	v_div_fmas_f32 v32, v32, v40, v33
	v_div_fixup_f32 v38, v32, v38, 1.0
	v_pk_mul_f32 v[34:35], v[34:35], v[38:39] op_sel_hi:[1,0]
	v_pk_mul_f32 v[30:31], v[30:31], v[38:39] op_sel_hi:[1,0]
	v_lshl_add_u64 v[40:41], s[2:3], 0, v[76:77]
	v_pk_mul_f32 v[32:33], v[188:189], v[30:31]
	v_pk_mul_f32 v[30:31], v[186:187], v[34:35]
	global_store_dwordx4 v[36:37], v[30:33], off nt
	v_pk_mul_f32 v[34:35], v[26:27], v[38:39] op_sel_hi:[1,0]
	v_pk_mul_f32 v[26:27], v[28:29], v[38:39] op_sel_hi:[1,0]
	v_pk_mul_f32 v[28:29], v[192:193], v[34:35]
	v_pk_mul_f32 v[26:27], v[190:191], v[26:27]
	global_store_dwordx4 v[36:37], v[26:29], off offset:64 nt
	v_pk_mul_f32 v[30:31], v[22:23], v[38:39] op_sel_hi:[1,0]
	v_pk_mul_f32 v[22:23], v[24:25], v[38:39] op_sel_hi:[1,0]
	v_pk_mul_f32 v[24:25], v[196:197], v[30:31]
	v_pk_mul_f32 v[22:23], v[194:195], v[22:23]
	global_store_dwordx4 v[36:37], v[22:25], off offset:512 nt
	v_pk_mul_f32 v[26:27], v[18:19], v[38:39] op_sel_hi:[1,0]
	v_pk_mul_f32 v[18:19], v[20:21], v[38:39] op_sel_hi:[1,0]
	v_pk_mul_f32 v[20:21], v[200:201], v[26:27]
	v_pk_mul_f32 v[18:19], v[198:199], v[18:19]
	global_store_dwordx4 v[36:37], v[18:21], off offset:576 nt
	s_nop 1
	global_load_dwordx4 v[18:21], v[40:41], off
	s_nop 0
	global_load_dwordx4 v[22:25], v[40:41], off offset:16
	global_load_dwordx4 v[26:29], v[40:41], off offset:32
	global_load_dwordx4 v[30:33], v[40:41], off offset:48
	s_waitcnt vmcnt(3)
	v_mov_b32_e32 v38, v19
	v_mov_b32_e32 v39, v20
	v_mov_b32_e32 v19, v21
	s_waitcnt vmcnt(2)
	v_mov_b32_e32 v20, v23
	v_mov_b32_e32 v21, v24
	v_mov_b32_e32 v23, v25
	v_pk_add_f32 v[18:19], v[38:39], v[18:19]
	v_pk_add_f32 v[20:21], v[20:21], v[22:23]
	v_pk_add_f32 v[18:19], v[18:19], v[18:19] op_sel:[0,1] op_sel_hi:[1,0]
	v_pk_add_f32 v[20:21], v[20:21], v[20:21] op_sel:[0,1] op_sel_hi:[1,0]
	s_waitcnt vmcnt(1)
	v_add_f32_e32 v24, v26, v27
	v_add_f32_e32 v26, v28, v29
	s_waitcnt vmcnt(0)
	v_mov_b32_e32 v25, v32
	v_mov_b32_e32 v27, v33
	v_mov_b32_e32 v19, v30
	v_mov_b32_e32 v21, v31
	v_pk_add_f32 v[22:23], v[24:25], v[26:27]
	v_pk_add_f32 v[18:19], v[18:19], v[20:21]
	s_nop 0
	v_pk_add_f32 v[18:19], v[18:19], v[22:23]
	s_nop 0
	v_add_f32_e32 v18, v18, v19
	v_fmac_f32_e32 v162, 0x3a800000, v18
	v_mul_f32_e32 v18, 0x4f800000, v162
	v_cmp_gt_f32_e32 vcc, s4, v162
	s_nop 1
	v_cndmask_b32_e32 v18, v162, v18, vcc
	v_sqrt_f32_e32 v19, v18
	s_nop 0
	v_add_u32_e32 v20, -1, v19
	v_add_u32_e32 v21, 1, v19
	v_fma_f32 v22, -v20, v19, v18
	v_fma_f32 v23, -v21, v19, v18
	v_cmp_ge_f32_e64 s[0:1], 0, v22
	s_nop 1
	v_cndmask_b32_e64 v19, v19, v20, s[0:1]
	v_cmp_lt_f32_e64 s[0:1], 0, v23
	s_nop 1
	v_cndmask_b32_e64 v19, v19, v21, s[0:1]
	v_mul_f32_e32 v20, 0x37800000, v19
	v_cndmask_b32_e32 v19, v19, v20, vcc
	v_cmp_class_f32_e32 vcc, v18, v163
	s_nop 1
	v_cndmask_b32_e32 v18, v19, v18, vcc
	v_div_scale_f32 v19, s[0:1], v18, v18, 1.0
	v_rcp_f32_e32 v20, v19
	v_div_scale_f32 v21, vcc, 1.0, v18, 1.0
	v_fma_f32 v22, -v19, v20, 1.0
	v_fmac_f32_e32 v20, v22, v20
	v_mul_f32_e32 v22, v21, v20
	v_fma_f32 v23, -v19, v22, v21
	v_fmac_f32_e32 v22, v23, v20
	v_fma_f32 v19, -v19, v22, v21
	v_div_fmas_f32 v19, v19, v20, v22
	v_div_fixup_f32 v18, v19, v18, 1.0
	v_pk_mul_f32 v[12:13], v[12:13], v[18:19] op_sel_hi:[1,0]
	v_pk_mul_f32 v[14:15], v[14:15], v[18:19] op_sel_hi:[1,0]
	v_pk_mul_f32 v[12:13], v[186:187], v[12:13]
	v_pk_mul_f32 v[14:15], v[188:189], v[14:15]
	global_store_dwordx4 v[16:17], v[12:15], off nt
	v_pk_mul_f32 v[10:11], v[10:11], v[18:19] op_sel_hi:[1,0]
	v_pk_mul_f32 v[8:9], v[8:9], v[18:19] op_sel_hi:[1,0]
	v_pk_mul_f32 v[6:7], v[6:7], v[18:19] op_sel_hi:[1,0]
	v_pk_mul_f32 v[4:5], v[4:5], v[18:19] op_sel_hi:[1,0]
	v_pk_mul_f32 v[2:3], v[2:3], v[18:19] op_sel_hi:[1,0]
	v_pk_mul_f32 v[0:1], v[0:1], v[18:19] op_sel_hi:[1,0]
	v_pk_mul_f32 v[8:9], v[190:191], v[8:9]
	v_pk_mul_f32 v[10:11], v[192:193], v[10:11]
	global_store_dwordx4 v[16:17], v[8:11], off offset:64 nt
	v_pk_mul_f32 v[4:5], v[194:195], v[4:5]
	v_pk_mul_f32 v[6:7], v[196:197], v[6:7]
	global_store_dwordx4 v[16:17], v[4:7], off offset:512 nt
	v_pk_mul_f32 v[0:1], v[198:199], v[0:1]
	v_pk_mul_f32 v[2:3], v[200:201], v[2:3]
	global_store_dwordx4 v[16:17], v[0:3], off offset:576 nt
